# code placement: everything behind P0 shifted by 4 bytes (one s_nop executed once per wave)
# speedup vs baseline: 1.0042x; 1.0042x over previous
.LBB0_87:
	s_nop 0
	s_load_dwordx16 s[36:51], s[0:1], 0x40
	v_writelane_b32 v254, s33, 39
	s_waitcnt lgkmcnt(0)
	v_writelane_b32 v254, s36, 40
	s_nop 1
	v_writelane_b32 v254, s37, 41
	v_writelane_b32 v254, s38, 42
	v_writelane_b32 v254, s39, 43
	v_writelane_b32 v254, s40, 44
	v_writelane_b32 v254, s41, 45
	v_writelane_b32 v254, s42, 46
	v_writelane_b32 v254, s43, 47
	v_writelane_b32 v254, s44, 48
	v_writelane_b32 v254, s45, 49
	v_writelane_b32 v254, s46, 50
	v_writelane_b32 v254, s47, 51
	v_writelane_b32 v254, s48, 52
	v_writelane_b32 v254, s49, 53
	v_writelane_b32 v254, s50, 54
	v_writelane_b32 v254, s51, 55
	s_nop 0
	v_readlane_b32 s0, v254, 6
	v_readlane_b32 s6, v254, 12
	v_readlane_b32 s1, v254, 7
	v_readlane_b32 s7, v254, 13
	s_add_u32 s0, s6, 0x3400000
	s_addc_u32 s1, s7, 0
	v_readlane_b32 s2, v254, 8
	v_readlane_b32 s3, v254, 9
	v_readlane_b32 s4, v254, 10
	v_readlane_b32 s5, v254, 11
	v_writelane_b32 v254, s0, 56
	s_nop 1
	v_writelane_b32 v254, s1, 57
	s_add_u32 s0, s6, 0x4600000
	s_addc_u32 s1, s7, 0
	v_writelane_b32 v254, s0, 58
	s_nop 1
	v_writelane_b32 v254, s1, 59
	s_add_u32 s0, s6, 0x5800000
	s_addc_u32 s1, s7, 0
	v_writelane_b32 v254, s0, 60
	s_nop 1
	v_writelane_b32 v254, s1, 61
	s_add_u32 s0, s6, 0x6a00000
	s_addc_u32 s1, s7, 0
	v_writelane_b32 v254, s0, 62
	s_nop 1
	v_writelane_b32 v254, s1, 63
	s_add_u32 s0, s6, 0x7c00000
	s_addc_u32 s1, s7, 0
	v_writelane_b32 v255, s0, 0
	s_nop 1
	v_writelane_b32 v255, s1, 1
	s_add_u32 s0, s6, 0x8e00000
	s_addc_u32 s1, s7, 0
	v_writelane_b32 v255, s0, 2
	s_nop 1
	v_writelane_b32 v255, s1, 3
	s_add_u32 s0, s6, 0xa000000
	s_addc_u32 s1, s7, 0
	v_writelane_b32 v255, s0, 4
	s_nop 1
	v_writelane_b32 v255, s1, 5
	s_add_u32 s0, s6, 0xb200000
	s_addc_u32 s1, s7, 0
	v_writelane_b32 v255, s0, 6
	s_cmp_lt_i32 s8, 2
	s_nop 0
	v_writelane_b32 v255, s1, 7
	s_cselect_b64 s[0:1], -1, 0
	s_cmp_gt_i32 s9, 1
	s_cselect_b64 s[2:3], -1, 0
	s_and_b64 s[0:1], s[0:1], s[2:3]
	s_andn2_b64 vcc, exec, s[0:1]
	s_cbranch_vccnz .LBB0_876
	s_cmpk_eq_i32 s89, 0x100
	s_cselect_b64 s[2:3], -1, 0
	v_mov_b32_e32 v10, v0
	s_cmpk_lt_i32 s88, 0x440
	v_cndmask_b32_e64 v1, 0, 1, s[2:3]
	s_cselect_b64 s[4:5], -1, 0
	v_readfirstlane_b32 s10, v10
	s_cmpk_gt_i32 s88, 0x43f
	v_cmp_ne_u32_e64 s[60:61], 1, v1
	s_cbranch_scc1 .LBB0_100
	s_and_b32 s0, s88, 7
	s_mulk_i32 s0, 0x88
	s_ashr_i32 s1, s88, 3
	s_and_b64 vcc, exec, s[60:61]
	s_add_i32 s6, s0, s1
	s_cbranch_vccnz .LBB0_95
	s_and_b32 s0, s6, -8
	s_cmpk_lg_i32 s0, 0x400
	s_cbranch_scc0 .LBB0_92
	s_sub_i32 s0, s6, 56
	s_cmpk_gt_i32 s6, 0x437
	s_cselect_b32 s7, s0, s6
	s_cbranch_execz .LBB0_93
	s_branch .LBB0_94
